# HGRN 1c loop: the 16 LDS reads of each 8-row block issued together (one wait instead of 16 exposed LDS round trips)
# speedup vs baseline: 1.0025x; 1.0008x over previous
; __device__ __forceinline__ float bf2f(bf16_t h) { return __uint_as_float(((unsigned)h) << 16); }
; __device__ __forceinline__ float flog_(float x) { return __builtin_amdgcn_logf(x) * 0.69314718056f; }
; __device__ __forceinline__ float silu(float x) { return x * sigm(x); }
; __device__ void mx_hgrn(const Params& P, int l, int item, char* lds) {
;     ...
;             {
;                 float g = hf ? R : 0.f;
; #pragma unroll 8
;                 for (int r = 0; r < 32; ++r) {
;                     const float fv = bf2f(kp[r * 136]);
;                     g += flog_(fv);
;                     const float e1 = __expf(fminf(g - R, 80.f));
;                     qp[r * 136] = f2bf(silu(bf2f(qp[r * 136])) * e1);
;                     kp[r * 136] = f2bf((1.f - fv) * __expf(fminf(R - g, 80.f)));
;                 }
.LBB0_521:
	v_add_u32_e32 v44, s28, v132
	ds_read_u16 v190, v44 offset:17408
	ds_read_u16 v191, v44
	ds_read_u16 v192, v44 offset:17680
	ds_read_u16 v193, v44 offset:272
	ds_read_u16 v194, v44 offset:17952
	ds_read_u16 v195, v44 offset:544
	ds_read_u16 v196, v44 offset:18224
	ds_read_u16 v197, v44 offset:816
	ds_read_u16 v198, v44 offset:18496
	ds_read_u16 v199, v44 offset:1088
	ds_read_u16 v200, v44 offset:18768
	ds_read_u16 v201, v44 offset:1360
	ds_read_u16 v202, v44 offset:19040
	ds_read_u16 v203, v44 offset:1632
	ds_read_u16 v204, v44 offset:19312
	ds_read_u16 v205, v44 offset:1904
	s_waitcnt lgkmcnt(0)
	s_addk_i32 s28, 0x880
	s_cmpk_eq_i32 s28, 0x2200
	v_lshlrev_b32_e32 v45, 16, v190
	v_log_f32_e32 v46, v45
	v_lshlrev_b32_e32 v47, 16, v191
	v_mul_f32_e32 v48, 0xbfb8aa3b, v47
	v_exp_f32_e32 v48, v48
	v_fmac_f32_e32 v43, 0x3f317218, v46
	v_sub_f32_e32 v46, v43, v42
	v_min_f32_e32 v46, 0x42a00000, v46
	v_add_f32_e32 v48, 1.0, v48
	v_mul_f32_e32 v46, 0x3fb8aa3b, v46
	v_rcp_f32_e32 v48, v48
	v_exp_f32_e32 v46, v46
	v_sub_f32_e32 v45, 1.0, v45
	v_mul_f32_e32 v47, v48, v47
	v_mul_f32_e32 v46, v47, v46
	v_cvt_pk_bf16_f32 v46, v46, s0
	ds_write_b16 v44, v46
	v_sub_f32_e32 v46, v42, v43
	v_min_f32_e32 v46, 0x42a00000, v46
	v_mul_f32_e32 v46, 0x3fb8aa3b, v46
	v_exp_f32_e32 v46, v46
	s_nop 0
	v_mul_f32_e32 v45, v45, v46
	v_cvt_pk_bf16_f32 v45, v45, s0
	ds_write_b16 v44, v45 offset:17408
	v_lshlrev_b32_e32 v47, 16, v193
	v_mul_f32_e32 v48, 0xbfb8aa3b, v47
	v_exp_f32_e32 v48, v48
	v_lshlrev_b32_e32 v45, 16, v192
	v_log_f32_e32 v46, v45
	v_add_f32_e32 v48, 1.0, v48
	v_rcp_f32_e32 v48, v48
	v_sub_f32_e32 v45, 1.0, v45
	v_fmac_f32_e32 v43, 0x3f317218, v46
	v_sub_f32_e32 v46, v43, v42
	v_min_f32_e32 v46, 0x42a00000, v46
	v_mul_f32_e32 v46, 0x3fb8aa3b, v46
	v_exp_f32_e32 v46, v46
	v_mul_f32_e32 v47, v48, v47
	v_mul_f32_e32 v46, v47, v46
	v_cvt_pk_bf16_f32 v46, v46, s0
	ds_write_b16 v44, v46 offset:272
	v_sub_f32_e32 v46, v42, v43
	v_min_f32_e32 v46, 0x42a00000, v46
	v_mul_f32_e32 v46, 0x3fb8aa3b, v46
	v_exp_f32_e32 v46, v46
	s_nop 0
	v_mul_f32_e32 v45, v45, v46
	v_cvt_pk_bf16_f32 v45, v45, s0
	ds_write_b16 v44, v45 offset:17680
	v_lshlrev_b32_e32 v47, 16, v195
	v_mul_f32_e32 v48, 0xbfb8aa3b, v47
	v_exp_f32_e32 v48, v48
	v_lshlrev_b32_e32 v45, 16, v194
	v_log_f32_e32 v46, v45
	v_add_f32_e32 v48, 1.0, v48
	v_rcp_f32_e32 v48, v48
	v_sub_f32_e32 v45, 1.0, v45
	v_fmac_f32_e32 v43, 0x3f317218, v46
	v_sub_f32_e32 v46, v43, v42
	v_min_f32_e32 v46, 0x42a00000, v46
	v_mul_f32_e32 v46, 0x3fb8aa3b, v46
	v_exp_f32_e32 v46, v46
	v_mul_f32_e32 v47, v48, v47
	v_mul_f32_e32 v46, v47, v46
	v_cvt_pk_bf16_f32 v46, v46, s0
	ds_write_b16 v44, v46 offset:544
	v_sub_f32_e32 v46, v42, v43
	v_min_f32_e32 v46, 0x42a00000, v46
	v_mul_f32_e32 v46, 0x3fb8aa3b, v46
	v_exp_f32_e32 v46, v46
	s_nop 0
	v_mul_f32_e32 v45, v45, v46
	v_cvt_pk_bf16_f32 v45, v45, s0
	ds_write_b16 v44, v45 offset:17952
	v_lshlrev_b32_e32 v47, 16, v197
	v_mul_f32_e32 v48, 0xbfb8aa3b, v47
	v_exp_f32_e32 v48, v48
	v_lshlrev_b32_e32 v45, 16, v196
	v_log_f32_e32 v46, v45
	v_add_f32_e32 v48, 1.0, v48
	v_rcp_f32_e32 v48, v48
	v_sub_f32_e32 v45, 1.0, v45
	v_fmac_f32_e32 v43, 0x3f317218, v46
	v_sub_f32_e32 v46, v43, v42
	v_min_f32_e32 v46, 0x42a00000, v46
	v_mul_f32_e32 v46, 0x3fb8aa3b, v46
	v_exp_f32_e32 v46, v46
	v_mul_f32_e32 v47, v48, v47
	v_mul_f32_e32 v46, v47, v46
	v_cvt_pk_bf16_f32 v46, v46, s0
	ds_write_b16 v44, v46 offset:816
	v_sub_f32_e32 v46, v42, v43
	v_min_f32_e32 v46, 0x42a00000, v46
	v_mul_f32_e32 v46, 0x3fb8aa3b, v46
	v_exp_f32_e32 v46, v46
	s_nop 0
	v_mul_f32_e32 v45, v45, v46
	v_cvt_pk_bf16_f32 v45, v45, s0
	ds_write_b16 v44, v45 offset:18224
	v_lshlrev_b32_e32 v47, 16, v199
	v_mul_f32_e32 v48, 0xbfb8aa3b, v47
	v_exp_f32_e32 v48, v48
	v_lshlrev_b32_e32 v45, 16, v198
	v_log_f32_e32 v46, v45
	v_add_f32_e32 v48, 1.0, v48
	v_rcp_f32_e32 v48, v48
	v_sub_f32_e32 v45, 1.0, v45
	v_fmac_f32_e32 v43, 0x3f317218, v46
	v_sub_f32_e32 v46, v43, v42
	v_min_f32_e32 v46, 0x42a00000, v46
	v_mul_f32_e32 v46, 0x3fb8aa3b, v46
	v_exp_f32_e32 v46, v46
	v_mul_f32_e32 v47, v48, v47
	v_mul_f32_e32 v46, v47, v46
	v_cvt_pk_bf16_f32 v46, v46, s0
	ds_write_b16 v44, v46 offset:1088
	v_sub_f32_e32 v46, v42, v43
	v_min_f32_e32 v46, 0x42a00000, v46
	v_mul_f32_e32 v46, 0x3fb8aa3b, v46
	v_exp_f32_e32 v46, v46
	s_nop 0
	v_mul_f32_e32 v45, v45, v46
	v_cvt_pk_bf16_f32 v45, v45, s0
	ds_write_b16 v44, v45 offset:18496
	v_lshlrev_b32_e32 v47, 16, v201
	v_mul_f32_e32 v48, 0xbfb8aa3b, v47
	v_exp_f32_e32 v48, v48
	v_lshlrev_b32_e32 v45, 16, v200
	v_log_f32_e32 v46, v45
	v_add_f32_e32 v48, 1.0, v48
	v_rcp_f32_e32 v48, v48
	v_sub_f32_e32 v45, 1.0, v45
	v_fmac_f32_e32 v43, 0x3f317218, v46
	v_sub_f32_e32 v46, v43, v42
	v_min_f32_e32 v46, 0x42a00000, v46
	v_mul_f32_e32 v46, 0x3fb8aa3b, v46
	v_exp_f32_e32 v46, v46
	v_mul_f32_e32 v47, v48, v47
	v_mul_f32_e32 v46, v47, v46
	v_cvt_pk_bf16_f32 v46, v46, s0
	ds_write_b16 v44, v46 offset:1360
	v_sub_f32_e32 v46, v42, v43
	v_min_f32_e32 v46, 0x42a00000, v46
	v_mul_f32_e32 v46, 0x3fb8aa3b, v46
	v_exp_f32_e32 v46, v46
	s_nop 0
	v_mul_f32_e32 v45, v45, v46
	v_cvt_pk_bf16_f32 v45, v45, s0
	ds_write_b16 v44, v45 offset:18768
	v_lshlrev_b32_e32 v47, 16, v203
	v_mul_f32_e32 v48, 0xbfb8aa3b, v47
	v_exp_f32_e32 v48, v48
	v_lshlrev_b32_e32 v45, 16, v202
	v_log_f32_e32 v46, v45
	v_add_f32_e32 v48, 1.0, v48
	v_rcp_f32_e32 v48, v48
	v_sub_f32_e32 v45, 1.0, v45
	v_fmac_f32_e32 v43, 0x3f317218, v46
	v_sub_f32_e32 v46, v43, v42
	v_min_f32_e32 v46, 0x42a00000, v46
	v_mul_f32_e32 v46, 0x3fb8aa3b, v46
	v_exp_f32_e32 v46, v46
	v_mul_f32_e32 v47, v48, v47
	v_mul_f32_e32 v46, v47, v46
	v_cvt_pk_bf16_f32 v46, v46, s0
	ds_write_b16 v44, v46 offset:1632
	v_sub_f32_e32 v46, v42, v43
	v_min_f32_e32 v46, 0x42a00000, v46
	v_mul_f32_e32 v46, 0x3fb8aa3b, v46
	v_exp_f32_e32 v46, v46
	s_nop 0
	v_mul_f32_e32 v45, v45, v46
	v_cvt_pk_bf16_f32 v45, v45, s0
	ds_write_b16 v44, v45 offset:19040
	v_lshlrev_b32_e32 v47, 16, v205
	v_mul_f32_e32 v48, 0xbfb8aa3b, v47
	v_exp_f32_e32 v48, v48
	v_lshlrev_b32_e32 v45, 16, v204
	v_log_f32_e32 v46, v45
	v_add_f32_e32 v48, 1.0, v48
	v_rcp_f32_e32 v48, v48
	v_sub_f32_e32 v45, 1.0, v45
	v_fmac_f32_e32 v43, 0x3f317218, v46
	v_sub_f32_e32 v46, v43, v42
	v_min_f32_e32 v46, 0x42a00000, v46
	v_mul_f32_e32 v46, 0x3fb8aa3b, v46
	v_exp_f32_e32 v46, v46
	v_mul_f32_e32 v47, v48, v47
	v_mul_f32_e32 v46, v47, v46
	v_cvt_pk_bf16_f32 v46, v46, s0
	ds_write_b16 v44, v46 offset:1904
	v_sub_f32_e32 v46, v42, v43
	v_min_f32_e32 v46, 0x42a00000, v46
	v_mul_f32_e32 v46, 0x3fb8aa3b, v46
	v_exp_f32_e32 v46, v46
	s_nop 0
	v_mul_f32_e32 v45, v45, v46
	v_cvt_pk_bf16_f32 v45, v45, s0
	ds_write_b16 v44, v45 offset:19312
	s_cbranch_scc0 .LBB0_521
; __device__ __forceinline__ float bf2f(bf16_t h) { return __uint_as_float(((unsigned)h) << 16); }
; __device__ void mx_hgrn(const Params& P, int l, int item, char* lds) {
;     ...
;                 const float eR = __expf(R);
;                 bf16_t* sp = ST + hf * 32 * 136 + dk;
; #pragma unroll 8
;                 for (int r = 0; r < 32; ++r) sp[r * 136] = f2bf(bf2f(sp[r * 136]) * eR);
;             }
;             __syncthreads();
	v_mul_f32_e32 v42, 0x3fb8aa3b, v42
	ds_read_u16 v43, v132 offset:54272
	ds_read_u16 v46, v132 offset:54544
	ds_read_u16 v44, v132 offset:54816
	ds_read_u16 v45, v132 offset:55088
	v_exp_f32_e32 v42, v42
	v_add_u32_e32 v147, v136, v83
	s_waitcnt lgkmcnt(2)
	v_lshlrev_b32_e32 v47, 16, v46
	v_lshlrev_b32_e32 v46, 16, v43
	s_waitcnt lgkmcnt(0)
	v_lshlrev_b32_e32 v45, 16, v45
	v_lshlrev_b32_e32 v44, 16, v44
	v_pk_mul_f32 v[46:47], v[42:43], v[46:47] op_sel_hi:[0,1]
	v_pk_mul_f32 v[44:45], v[42:43], v[44:45] op_sel_hi:[0,1]
	v_cvt_pk_bf16_f32 v46, v46, s0
	v_cvt_pk_bf16_f32 v43, v45, s0
	v_cvt_pk_bf16_f32 v44, v44, s0
	v_cvt_pk_bf16_f32 v45, v47, s0
	ds_write_b16 v132, v46 offset:54272
	ds_write_b16 v132, v45 offset:54544
	ds_write_b16 v132, v44 offset:54816
	ds_write_b16 v132, v43 offset:55088
	ds_read_u16 v43, v132 offset:55360
	ds_read_u16 v46, v132 offset:55632
	ds_read_u16 v44, v132 offset:55904
	ds_read_u16 v45, v132 offset:56176
	v_add_u32_e32 v164, v136, v85
	s_lshl_b32 s28, s34, 6
	s_waitcnt lgkmcnt(2)
	v_lshlrev_b32_e32 v47, 16, v46
	v_lshlrev_b32_e32 v46, 16, v43
	s_waitcnt lgkmcnt(0)
	v_lshlrev_b32_e32 v45, 16, v45
	v_lshlrev_b32_e32 v44, 16, v44
	v_pk_mul_f32 v[46:47], v[42:43], v[46:47] op_sel_hi:[0,1]
	v_pk_mul_f32 v[44:45], v[42:43], v[44:45] op_sel_hi:[0,1]
	v_cvt_pk_bf16_f32 v46, v46, s0
	v_cvt_pk_bf16_f32 v43, v45, s0
	v_cvt_pk_bf16_f32 v44, v44, s0
	v_cvt_pk_bf16_f32 v45, v47, s0
	ds_write_b16 v132, v46 offset:55360
	ds_write_b16 v132, v45 offset:55632
	ds_write_b16 v132, v44 offset:55904
	ds_write_b16 v132, v43 offset:56176
	ds_read_u16 v43, v132 offset:56448
	ds_read_u16 v46, v132 offset:56720
	ds_read_u16 v44, v132 offset:56992
	ds_read_u16 v45, v132 offset:57264
	s_sub_i32 s26, 0x7c0, s28
	s_and_b64 s[34:35], vcc, exec
	s_waitcnt lgkmcnt(2)
	v_lshlrev_b32_e32 v47, 16, v46
	v_lshlrev_b32_e32 v46, 16, v43
	s_waitcnt lgkmcnt(0)
	v_lshlrev_b32_e32 v45, 16, v45
	v_lshlrev_b32_e32 v44, 16, v44
	v_pk_mul_f32 v[46:47], v[42:43], v[46:47] op_sel_hi:[0,1]
	v_pk_mul_f32 v[44:45], v[42:43], v[44:45] op_sel_hi:[0,1]
	v_cvt_pk_bf16_f32 v46, v46, s0
	v_cvt_pk_bf16_f32 v43, v45, s0
	v_cvt_pk_bf16_f32 v44, v44, s0
	v_cvt_pk_bf16_f32 v45, v47, s0
	ds_write_b16 v132, v46 offset:56448
	ds_write_b16 v132, v45 offset:56720
	ds_write_b16 v132, v44 offset:56992
	ds_write_b16 v132, v43 offset:57264
	ds_read_u16 v43, v132 offset:57536
	ds_read_u16 v46, v132 offset:57808
	ds_read_u16 v44, v132 offset:58080
	ds_read_u16 v45, v132 offset:58352
	s_cselect_b32 s29, s28, s26
	s_cmp_eq_u32 s21, 32
	s_waitcnt lgkmcnt(2)
	v_lshlrev_b32_e32 v47, 16, v46
	v_lshlrev_b32_e32 v46, 16, v43
	s_waitcnt lgkmcnt(0)
	v_lshlrev_b32_e32 v45, 16, v45
	v_lshlrev_b32_e32 v44, 16, v44
	v_pk_mul_f32 v[46:47], v[42:43], v[46:47] op_sel_hi:[0,1]
	v_pk_mul_f32 v[44:45], v[42:43], v[44:45] op_sel_hi:[0,1]
	v_cvt_pk_bf16_f32 v46, v46, s0
	v_cvt_pk_bf16_f32 v43, v45, s0
	v_cvt_pk_bf16_f32 v44, v44, s0
	v_cvt_pk_bf16_f32 v45, v47, s0
	ds_write_b16 v132, v46 offset:57536
	ds_write_b16 v132, v45 offset:57808
	ds_write_b16 v132, v44 offset:58080
	ds_write_b16 v132, v43 offset:58352
	ds_read_u16 v43, v132 offset:58624
	ds_read_u16 v46, v132 offset:58896
	ds_read_u16 v44, v132 offset:59168
	ds_read_u16 v45, v132 offset:59440
	s_mov_b32 s34, s21
	s_waitcnt lgkmcnt(2)
	v_lshlrev_b32_e32 v47, 16, v46
	v_lshlrev_b32_e32 v46, 16, v43
	s_waitcnt lgkmcnt(0)
	v_lshlrev_b32_e32 v45, 16, v45
	v_lshlrev_b32_e32 v44, 16, v44
	v_pk_mul_f32 v[46:47], v[42:43], v[46:47] op_sel_hi:[0,1]
	v_pk_mul_f32 v[44:45], v[42:43], v[44:45] op_sel_hi:[0,1]
	v_cvt_pk_bf16_f32 v46, v46, s0
	v_cvt_pk_bf16_f32 v43, v45, s0
	v_cvt_pk_bf16_f32 v44, v44, s0
	v_cvt_pk_bf16_f32 v45, v47, s0
	ds_write_b16 v132, v46 offset:58624
	ds_write_b16 v132, v45 offset:58896
	ds_write_b16 v132, v44 offset:59168
	ds_write_b16 v132, v43 offset:59440
	ds_read_u16 v43, v132 offset:59712
	ds_read_u16 v46, v132 offset:59984
	ds_read_u16 v44, v132 offset:60256
	ds_read_u16 v45, v132 offset:60528
	s_waitcnt lgkmcnt(2)
	v_lshlrev_b32_e32 v47, 16, v46
	v_lshlrev_b32_e32 v46, 16, v43
	s_waitcnt lgkmcnt(0)
	v_lshlrev_b32_e32 v45, 16, v45
	v_lshlrev_b32_e32 v44, 16, v44
	v_pk_mul_f32 v[46:47], v[42:43], v[46:47] op_sel_hi:[0,1]
	v_pk_mul_f32 v[44:45], v[42:43], v[44:45] op_sel_hi:[0,1]
	v_cvt_pk_bf16_f32 v46, v46, s0
	v_cvt_pk_bf16_f32 v43, v45, s0
	v_cvt_pk_bf16_f32 v44, v44, s0
	v_cvt_pk_bf16_f32 v45, v47, s0
	ds_write_b16 v132, v46 offset:59712
	ds_write_b16 v132, v45 offset:59984
	ds_write_b16 v132, v44 offset:60256
	ds_write_b16 v132, v43 offset:60528
	ds_read_u16 v43, v132 offset:60800
	ds_read_u16 v46, v132 offset:61072
	ds_read_u16 v44, v132 offset:61344
	ds_read_u16 v45, v132 offset:61616
	s_waitcnt lgkmcnt(2)
	v_lshlrev_b32_e32 v47, 16, v46
	v_lshlrev_b32_e32 v46, 16, v43
	s_waitcnt lgkmcnt(0)
	v_lshlrev_b32_e32 v45, 16, v45
	v_lshlrev_b32_e32 v44, 16, v44
	v_pk_mul_f32 v[46:47], v[42:43], v[46:47] op_sel_hi:[0,1]
	v_pk_mul_f32 v[44:45], v[42:43], v[44:45] op_sel_hi:[0,1]
	v_cvt_pk_bf16_f32 v46, v46, s0
	v_cvt_pk_bf16_f32 v43, v45, s0
	v_cvt_pk_bf16_f32 v44, v44, s0
	v_cvt_pk_bf16_f32 v45, v47, s0
	ds_write_b16 v132, v46 offset:60800
	ds_write_b16 v132, v45 offset:61072
	ds_write_b16 v132, v44 offset:61344
	ds_write_b16 v132, v43 offset:61616
	ds_read_u16 v43, v132 offset:61888
	ds_read_u16 v46, v132 offset:62160
	ds_read_u16 v44, v132 offset:62432
	ds_read_u16 v45, v132 offset:62704
	s_waitcnt lgkmcnt(2)
	v_lshlrev_b32_e32 v47, 16, v46
	s_waitcnt lgkmcnt(1)
	v_lshlrev_b32_e32 v44, 16, v44
	s_waitcnt lgkmcnt(0)
	v_lshlrev_b32_e32 v45, 16, v45
	v_lshlrev_b32_e32 v46, 16, v43
	v_pk_mul_f32 v[46:47], v[42:43], v[46:47] op_sel_hi:[0,1]
	v_pk_mul_f32 v[42:43], v[42:43], v[44:45] op_sel_hi:[0,1]
	v_cvt_pk_bf16_f32 v43, v43, s0
	v_cvt_pk_bf16_f32 v42, v42, s0
	v_cvt_pk_bf16_f32 v44, v47, s0
	v_cvt_pk_bf16_f32 v45, v46, s0
	ds_write_b16 v132, v45 offset:61888
	ds_write_b16 v132, v44 offset:62160
	ds_write_b16 v132, v42 offset:62432
	ds_write_b16 v132, v43 offset:62704
	s_waitcnt lgkmcnt(0)
	s_barrier
; __device__ __forceinline__ unsigned pack2(float a, float b) { const f32x2n v = {a, b}; const bf16x2n h = __builtin_convertvector(v, bf16x2n); return __builtin_bit_cast(unsigned, h); }
; __device__ __forceinline__ f32x4 mfma16(bf16x8 a, bf16x8 b, f32x4 c) { return __builtin_amdgcn_mfma_f32_16x16x32_bf16(a, b, c, 0, 0, 0); }
; __device__ void mx_hgrn(const Params& P, int l, int item, char* lds) {
;     ...
;             f32x4 oacc[4];
;             unsigned kw[16];
;             {
;                 f32x4 aacc[4];
; #pragma unroll
;                 for (int st = 0; st < 4; ++st) { aacc[st] = (f32x4){0.f, 0.f, 0.f, 0.f}; oacc[st] = (f32x4){0.f, 0.f, 0.f, 0.f}; }
; #pragma unroll
;                 for (int ks = 0; ks < 4; ++ks) {
;                     const bf16x8 qf = ldfrag(QT + i * 136 + ks * 32 + fq * 8);
; #pragma unroll
;                     for (int st = 0; st < 4; ++st) aacc[st] = mfma16(ldfrag(KT + (st * 16 + fr) * 136 + ks * 32 + fq * 8), qf, aacc[st]);
; #pragma unroll
;                     for (int dt = 0; dt < 4; ++dt) oacc[dt] = mfma16(ldfrag(ST + (dt * 16 + fr) * 136 + ks * 32 + fq * 8), qf, oacc[dt]);
;                 }
; #pragma unroll
;                 for (int st = 0; st < 4; ++st) {
;                     float a[4];
; #pragma unroll
;                     for (int jj = 0; jj < 4; ++jj) a[jj] = (st * 16 + fq * 4 + jj <= i) ? aacc[st][jj] : 0.f;
;                     *(u32x2*)(ATT + i * 72 + st * 16 + fq * 4) = (u32x2){pack2(a[0], a[1]), pack2(a[2], a[3])};
;                 }
; #pragma unroll
;                 for (int r = 0; r < 16; ++r) kw[r] = (unsigned)kp[(2 * r) * 136] | ((unsigned)kp[(2 * r + 1) * 136] << 16);
	ds_read_b128 v[42:45], v135
	ds_read_b128 v[62:65], v147 offset:54272
	ds_read_b128 v[46:49], v147 offset:17408
	ds_read_b128 v[50:53], v147 offset:21760
	ds_read_b128 v[54:57], v147 offset:26112
	ds_read_b128 v[58:61], v147 offset:30464
	ds_read_b128 v[66:69], v147 offset:58624
	ds_read_b128 v[70:73], v147 offset:62976
	ds_read_b128 v[120:123], v164 offset:62976
	s_waitcnt lgkmcnt(6)
	v_mfma_f32_16x16x32_bf16 v[46:49], v[46:49], v[42:45], 0
	s_waitcnt lgkmcnt(5)
	v_mfma_f32_16x16x32_bf16 v[50:53], v[50:53], v[42:45], 0
	s_waitcnt lgkmcnt(4)
	v_mfma_f32_16x16x32_bf16 v[54:57], v[54:57], v[42:45], 0
	s_waitcnt lgkmcnt(3)
	v_mfma_f32_16x16x32_bf16 v[58:61], v[58:61], v[42:45], 0
	v_mfma_f32_16x16x32_bf16 v[62:65], v[62:65], v[42:45], 0
	s_waitcnt lgkmcnt(2)
	v_mfma_f32_16x16x32_bf16 v[66:69], v[66:69], v[42:45], 0
	s_waitcnt lgkmcnt(1)
	v_mfma_f32_16x16x32_bf16 v[70:73], v[70:73], v[42:45], 0
	s_waitcnt lgkmcnt(0)
	v_mfma_f32_16x16x32_bf16 v[42:45], v[120:123], v[42:45], 0
	ds_read_b128 v[120:123], v135 offset:64
	ds_read_b128 v[148:151], v147 offset:17472
	s_waitcnt lgkmcnt(0)
	v_mfma_f32_16x16x32_bf16 v[46:49], v[148:151], v[120:123], v[46:49]
	ds_read_b128 v[148:151], v147 offset:21824
	s_waitcnt lgkmcnt(0)
	v_mfma_f32_16x16x32_bf16 v[50:53], v[148:151], v[120:123], v[50:53]
	ds_read_b128 v[148:151], v147 offset:26176
	s_waitcnt lgkmcnt(0)
	v_mfma_f32_16x16x32_bf16 v[54:57], v[148:151], v[120:123], v[54:57]
	ds_read_b128 v[148:151], v147 offset:30528
	s_waitcnt lgkmcnt(0)
	v_mfma_f32_16x16x32_bf16 v[58:61], v[148:151], v[120:123], v[58:61]
	ds_read_b128 v[148:151], v147 offset:54336
	s_waitcnt lgkmcnt(0)
	v_mfma_f32_16x16x32_bf16 v[62:65], v[148:151], v[120:123], v[62:65]
	ds_read_b128 v[148:151], v147 offset:58688
	s_waitcnt lgkmcnt(0)
	v_mfma_f32_16x16x32_bf16 v[66:69], v[148:151], v[120:123], v[66:69]
	ds_read_b128 v[148:151], v147 offset:63040
	s_waitcnt lgkmcnt(0)
	v_mfma_f32_16x16x32_bf16 v[70:73], v[148:151], v[120:123], v[70:73]
	ds_read_b128 v[148:151], v164 offset:63040
	s_waitcnt lgkmcnt(0)
	v_mfma_f32_16x16x32_bf16 v[42:45], v[148:151], v[120:123], v[42:45]
	ds_read_b128 v[120:123], v135 offset:128
	ds_read_b128 v[148:151], v147 offset:17536
	s_waitcnt lgkmcnt(0)
	v_mfma_f32_16x16x32_bf16 v[46:49], v[148:151], v[120:123], v[46:49]
	ds_read_b128 v[148:151], v147 offset:21888
	s_waitcnt lgkmcnt(0)
	v_mfma_f32_16x16x32_bf16 v[50:53], v[148:151], v[120:123], v[50:53]
	ds_read_b128 v[148:151], v147 offset:26240
	s_waitcnt lgkmcnt(0)
	v_mfma_f32_16x16x32_bf16 v[54:57], v[148:151], v[120:123], v[54:57]
	ds_read_b128 v[148:151], v147 offset:30592
	s_waitcnt lgkmcnt(0)
	v_mfma_f32_16x16x32_bf16 v[58:61], v[148:151], v[120:123], v[58:61]
	ds_read_b128 v[148:151], v147 offset:54400
	s_waitcnt lgkmcnt(0)
	v_mfma_f32_16x16x32_bf16 v[62:65], v[148:151], v[120:123], v[62:65]
	ds_read_b128 v[148:151], v147 offset:58752
	s_waitcnt lgkmcnt(0)
	v_mfma_f32_16x16x32_bf16 v[66:69], v[148:151], v[120:123], v[66:69]
	ds_read_b128 v[148:151], v147 offset:63104
	s_waitcnt lgkmcnt(0)
	v_mfma_f32_16x16x32_bf16 v[70:73], v[148:151], v[120:123], v[70:73]
	ds_read_b128 v[148:151], v164 offset:63104
	s_waitcnt lgkmcnt(0)
	v_mfma_f32_16x16x32_bf16 v[120:123], v[148:151], v[120:123], v[42:45]
	ds_read_b128 v[148:151], v135 offset:192
	s_nop 1
	ds_read_b128 v[42:45], v147 offset:17600
	s_waitcnt lgkmcnt(0)
	v_mfma_f32_16x16x32_bf16 v[152:155], v[42:45], v[148:151], v[46:49]
	ds_read_b128 v[42:45], v147 offset:21952
	s_nop 1
	ds_read_b128 v[46:49], v147 offset:58816
	s_waitcnt lgkmcnt(1)
	v_mfma_f32_16x16x32_bf16 v[156:159], v[42:45], v[148:151], v[50:53]
	ds_read_b128 v[42:45], v147 offset:26304
	s_nop 1
	ds_read_b128 v[50:53], v147 offset:63168
	s_waitcnt lgkmcnt(1)
	v_mfma_f32_16x16x32_bf16 v[160:163], v[42:45], v[148:151], v[54:57]
	ds_read_b128 v[42:45], v147 offset:30656
	s_nop 1
	ds_read_b128 v[54:57], v164 offset:63168
	s_waitcnt lgkmcnt(1)
	v_mfma_f32_16x16x32_bf16 v[58:61], v[42:45], v[148:151], v[58:61]
	ds_read_b128 v[42:45], v147 offset:54464
	v_add_u32_e32 v147, v137, v74
	s_nop 5
	v_cndmask_b32_e64 v58, v58, 0, s[64:65]
	s_waitcnt lgkmcnt(0)
	v_mfma_f32_16x16x32_bf16 v[42:45], v[42:45], v[148:151], v[62:65]
	s_nop 2
	v_cndmask_b32_e64 v62, v152, 0, s[40:41]
	v_cndmask_b32_e64 v63, 0, v153, s[42:43]
	v_cndmask_b32_e64 v64, v154, 0, s[44:45]
	v_cndmask_b32_e64 v65, v155, 0, s[46:47]
	v_mfma_f32_16x16x32_bf16 v[46:49], v[46:49], v[148:151], v[66:69]
	v_cvt_pk_bf16_f32 v62, v62, v63
	v_cvt_pk_bf16_f32 v63, v64, v65
	v_cndmask_b32_e64 v64, v156, 0, s[48:49]
	v_cndmask_b32_e64 v65, v157, 0, s[50:51]
	v_cndmask_b32_e64 v66, v158, 0, s[52:53]
	v_cndmask_b32_e64 v67, v159, 0, s[54:55]
	v_cvt_pk_bf16_f32 v64, v64, v65
	v_cvt_pk_bf16_f32 v65, v66, v67
	v_add_u32_e32 v66, 0x8800, v137
	ds_write2_b64 v66, v[62:63], v[64:65] offset0:128 offset1:132
	v_cndmask_b32_e64 v62, v160, 0, s[56:57]
	v_cndmask_b32_e64 v63, v161, 0, s[58:59]
	v_cndmask_b32_e64 v64, v162, 0, s[60:61]
	v_cndmask_b32_e64 v65, v163, 0, s[62:63]
	v_cndmask_b32_e64 v59, v59, 0, s[66:67]
	v_cndmask_b32_e64 v60, v60, 0, s[68:69]
	v_cndmask_b32_e64 v61, v61, 0, s[70:71]
	v_cvt_pk_bf16_f32 v62, v62, v63
	v_cvt_pk_bf16_f32 v63, v64, v65
	v_cvt_pk_bf16_f32 v58, v58, v59
	v_cvt_pk_bf16_f32 v59, v60, v61
	ds_write2_b64 v66, v[62:63], v[58:59] offset0:136 offset1:140
	ds_read_u16 v58, v132 offset:17408
	ds_read_u16 v59, v132 offset:17680
	v_mfma_f32_16x16x32_bf16 v[50:53], v[50:53], v[148:151], v[70:73]
	s_waitcnt lgkmcnt(0)
	v_lshl_or_b32 v58, v59, 16, v58
	ds_read_u16 v59, v132 offset:17952
	ds_read_u16 v60, v132 offset:18224
	v_mfma_f32_16x16x32_bf16 v[54:57], v[54:57], v[148:151], v[120:123]
	s_waitcnt lgkmcnt(0)
; __device__ __forceinline__ unsigned pack2(float a, float b) { const f32x2n v = {a, b}; const bf16x2n h = __builtin_convertvector(v, bf16x2n); return __builtin_bit_cast(unsigned, h); }
; __device__ __forceinline__ f32x4 mfma16(bf16x8 a, bf16x8 b, f32x4 c) { return __builtin_amdgcn_mfma_f32_16x16x32_bf16(a, b, c, 0, 0, 0); }
; __device__ void mx_hgrn(const Params& P, int l, int item, char* lds) {
;     ...
;                 for (int r = 0; r < 16; ++r) kw[r] = (unsigned)kp[(2 * r) * 136] | ((unsigned)kp[(2 * r + 1) * 136] << 16);
;             }
;             __syncthreads();
;             {
;                 u32x4* dst = (u32x4*)(KT + dk * 72 + hf * 32);
;                 dst[0] = (u32x4){kw[0], kw[1], kw[2], kw[3]}; dst[1] = (u32x4){kw[4], kw[5], kw[6], kw[7]};
;                 dst[2] = (u32x4){kw[8], kw[9], kw[10], kw[11]}; dst[3] = (u32x4){kw[12], kw[13], kw[14], kw[15]};
;             }
;             __syncthreads();
;             {
; #pragma unroll
;                 for (int ks = 0; ks < 2; ++ks) {
;                     const bf16x8 af = ldfrag(ATT + i * 72 + ks * 32 + fq * 8);
; #pragma unroll
;                     for (int dt = 0; dt < 4; ++dt) oacc[dt] = mfma16(ldfrag(VT + (dt * 16 + fr) * 72 + ks * 32 + fq * 8), af, oacc[dt]);
;                 }
;                 const int t = TROW(i);
;                 bf16_t* yp = YD + (size_t)t * 512 + fq * 4;
; #pragma unroll
;                 for (int dt = 0; dt < 4; ++dt) {
;                     f32x4 v = oacc[dt];
;                     *(u32x2*)(yp + dt * 16) = (u32x2){pack2(v[0], v[1]), pack2(v[2], v[3])};
;                 }
;             }
; #pragma unroll
;             for (int a = 0; a < 2; ++a) {
;                 const int ktile = 2 * wid + a;
;                 f32x4 e1, e2;
; #pragma unroll
;                 for (int jj = 0; jj < 4; ++jj) { const int dkk = ktile * 16 + fq * 4 + jj; e1[jj] = __expf(TOT[dkk]); e2[jj] = __expf(TOT[128 + dkk]); }
; #pragma unroll
;                 for (int dt = 0; dt < 4; ++dt) Sacc[a][dt] *= e1;
	v_lshl_or_b32 v59, v60, 16, v59
	ds_read_u16 v60, v132 offset:18496
	ds_read_u16 v61, v132 offset:18768
	s_waitcnt lgkmcnt(0)
	v_lshl_or_b32 v60, v61, 16, v60
	ds_read_u16 v61, v132 offset:19040
	ds_read_u16 v62, v132 offset:19312
	s_waitcnt lgkmcnt(0)
	v_lshl_or_b32 v61, v62, 16, v61
	ds_read_u16 v62, v132 offset:19584
	ds_read_u16 v63, v132 offset:19856
	s_waitcnt lgkmcnt(0)
	v_lshl_or_b32 v62, v63, 16, v62
	ds_read_u16 v63, v132 offset:20128
	ds_read_u16 v64, v132 offset:20400
	s_waitcnt lgkmcnt(0)
	v_lshl_or_b32 v63, v64, 16, v63
	ds_read_u16 v64, v132 offset:20672
	ds_read_u16 v65, v132 offset:20944
	s_waitcnt lgkmcnt(0)
	v_lshl_or_b32 v64, v65, 16, v64
	ds_read_u16 v65, v132 offset:21216
	ds_read_u16 v66, v132 offset:21488
	s_waitcnt lgkmcnt(0)
	v_lshl_or_b32 v65, v66, 16, v65
	ds_read_u16 v66, v132 offset:21760
	ds_read_u16 v67, v132 offset:22032
	s_waitcnt lgkmcnt(0)
	v_lshl_or_b32 v66, v67, 16, v66
	ds_read_u16 v67, v132 offset:22304
	ds_read_u16 v68, v132 offset:22576
	s_waitcnt lgkmcnt(0)
	v_lshl_or_b32 v67, v68, 16, v67
	ds_read_u16 v68, v132 offset:22848
	ds_read_u16 v69, v132 offset:23120
	s_waitcnt lgkmcnt(0)
	v_lshl_or_b32 v68, v69, 16, v68
	ds_read_u16 v69, v132 offset:23392
	ds_read_u16 v70, v132 offset:23664
	s_waitcnt lgkmcnt(0)
	v_lshl_or_b32 v69, v70, 16, v69
	ds_read_u16 v70, v132 offset:23936
	ds_read_u16 v71, v132 offset:24208
	s_waitcnt lgkmcnt(0)
	v_lshl_or_b32 v70, v71, 16, v70
	ds_read_u16 v71, v132 offset:24480
	ds_read_u16 v72, v132 offset:24752
	s_waitcnt lgkmcnt(0)
	v_lshl_or_b32 v71, v72, 16, v71
	ds_read_u16 v72, v132 offset:25024
	ds_read_u16 v73, v132 offset:25296
	s_waitcnt lgkmcnt(0)
	v_lshl_or_b32 v72, v73, 16, v72
	ds_read_u16 v73, v132 offset:25568
	ds_read_u16 v120, v132 offset:25840
	s_waitcnt lgkmcnt(0)
	s_barrier
	v_lshl_or_b32 v73, v120, 16, v73
	ds_write_b128 v141, v[58:61] offset:17408
	ds_write_b128 v141, v[62:65] offset:17424
	ds_write_b128 v141, v[66:69] offset:17440
	ds_write_b128 v141, v[70:73] offset:17456
	s_waitcnt lgkmcnt(0)
	s_barrier
	ds_read_b128 v[120:123], v147 offset:35840
	ds_read_b128 v[58:61], v142 offset:45056
	ds_read_b128 v[62:65], v142 offset:47360
	ds_read_b128 v[66:69], v142 offset:49664
	ds_read_b128 v[70:73], v142 offset:51968
	s_waitcnt lgkmcnt(3)
	v_mfma_f32_16x16x32_bf16 v[148:151], v[58:61], v[120:123], v[42:45]
	ds_read_b128 v[160:163], v147 offset:35904
	s_nop 1
	ds_read_b128 v[42:45], v142 offset:45120
	v_sub_u32_e32 v147, s29, v126
	v_add_u32_e32 v147, 63, v147
	s_waitcnt lgkmcnt(4)
	v_mfma_f32_16x16x32_bf16 v[152:155], v[62:65], v[120:123], v[46:49]
	s_nop 2
	ds_read_b128 v[46:49], v142 offset:47424
	s_waitcnt lgkmcnt(4)
	v_mfma_f32_16x16x32_bf16 v[156:159], v[66:69], v[120:123], v[50:53]
	s_waitcnt lgkmcnt(3)
	v_mfma_f32_16x16x32_bf16 v[120:123], v[70:73], v[120:123], v[54:57]
	s_nop 0
	ds_read_b128 v[50:53], v142 offset:49728
	s_nop 0
	ds_read_b128 v[54:57], v142 offset:52032
	s_waitcnt lgkmcnt(3)
	v_mfma_f32_16x16x32_bf16 v[148:151], v[42:45], v[160:163], v[148:151]
	s_waitcnt lgkmcnt(2)
	v_mfma_f32_16x16x32_bf16 v[152:155], v[46:49], v[160:163], v[152:155]
	s_waitcnt lgkmcnt(1)
	v_mfma_f32_16x16x32_bf16 v[156:159], v[50:53], v[160:163], v[156:159]
	s_nop 3
	v_cvt_pk_bf16_f32 v148, v148, v149
	v_cvt_pk_bf16_f32 v149, v150, v151
	s_waitcnt lgkmcnt(0)
	v_mfma_f32_16x16x32_bf16 v[120:123], v[54:57], v[160:163], v[120:123]
	v_add_u32_e32 v160, s28, v126
	v_cndmask_b32_e32 v160, v147, v160, vcc
	v_ashrrev_i32_e32 v161, 31, v160
	v_lshlrev_b64 v[160:161], 10, v[160:161]
	v_lshl_add_u64 v[160:161], v[76:77], 0, v[160:161]
	global_store_dwordx2 v[160:161], v[148:149], off
	v_cvt_pk_bf16_f32 v148, v152, v153
	v_cvt_pk_bf16_f32 v149, v154, v155
	v_cvt_pk_bf16_f32 v120, v120, v121
	v_cvt_pk_bf16_f32 v121, v122, v123
	global_store_dwordx2 v[160:161], v[148:149], off offset:32
	v_cvt_pk_bf16_f32 v148, v156, v157
	v_cvt_pk_bf16_f32 v149, v158, v159
	global_store_dwordx2 v[160:161], v[120:121], off offset:96
	ds_read_b128 v[120:123], v143
	global_store_dwordx2 v[160:161], v[148:149], off offset:64
	ds_read_b128 v[148:151], v143 offset:512
	s_waitcnt lgkmcnt(1)
	v_mul_f32_e32 v120, 0x3fb8aa3b, v120
	v_mul_f32_e32 v121, 0x3fb8aa3b, v121
	v_mul_f32_e32 v122, 0x3fb8aa3b, v122
	v_mul_f32_e32 v123, 0x3fb8aa3b, v123
	v_exp_f32_e32 v152, v120
	s_waitcnt lgkmcnt(0)
	v_mul_f32_e32 v120, 0x3fb8aa3b, v148
	v_exp_f32_e32 v153, v121
	v_mul_f32_e32 v121, 0x3fb8aa3b, v149
	v_exp_f32_e32 v148, v122
	v_exp_f32_e32 v149, v123
	v_mul_f32_e32 v122, 0x3fb8aa3b, v150
	v_mul_f32_e32 v123, 0x3fb8aa3b, v151
	v_pk_mul_f32 v[88:89], v[88:89], v[152:153]
	v_pk_mul_f32 v[90:91], v[90:91], v[148:149]
	v_pk_mul_f32 v[94:95], v[94:95], v[148:149]
	v_pk_mul_f32 v[102:103], v[102:103], v[148:149]
	v_pk_mul_f32 v[110:111], v[110:111], v[148:149]
	ds_read_b128 v[148:151], v144 offset:17408
	s_waitcnt lgkmcnt(0)
; __device__ __forceinline__ unsigned pack2(float a, float b) { const f32x2n v = {a, b}; const bf16x2n h = __builtin_convertvector(v, bf16x2n); return __builtin_bit_cast(unsigned, h); }
; __device__ __forceinline__ f32x4 mfma16(bf16x8 a, bf16x8 b, f32x4 c) { return __builtin_amdgcn_mfma_f32_16x16x32_bf16(a, b, c, 0, 0, 0); }
; __device__ void mx_hgrn(const Params& P, int l, int item, char* lds) {
;     ...
;             for (int a = 0; a < 2; ++a) {
;                 const int ktile = 2 * wid + a;
;                 f32x4 e1, e2;
; #pragma unroll
;                 for (int jj = 0; jj < 4; ++jj) { const int dkk = ktile * 16 + fq * 4 + jj; e1[jj] = __expf(TOT[dkk]); e2[jj] = __expf(TOT[128 + dkk]); }
; #pragma unroll
;                 for (int dt = 0; dt < 4; ++dt) Sacc[a][dt] *= e1;
; #pragma unroll
;                 for (int ks = 0; ks < 2; ++ks) {
;                     const bf16x8 kf = ldfrag(KT + (ktile * 16 + fr) * 72 + ks * 32 + fq * 8);
; #pragma unroll
;                     for (int dt = 0; dt < 4; ++dt) Sacc[a][dt] = mfma16(kf, ldfrag(VT + (dt * 16 + fr) * 72 + ks * 32 + fq * 8), Sacc[a][dt]);
;                 }
; #pragma unroll
;                 for (int dt = 0; dt < 4; ++dt) {
;                     Sacc[a][dt] *= e2;
;                     *(u32x2*)(ST + (dt * 16 + fr) * 136 + ktile * 16 + fq * 4) = (u32x2){pack2(Sacc[a][dt][0], Sacc[a][dt][1]), pack2(Sacc[a][dt][2], Sacc[a][dt][3])};
;                 }
;             }
;             __syncthreads();
	v_mfma_f32_16x16x32_bf16 v[58:61], v[148:151], v[58:61], v[88:91]
	s_nop 2
	ds_read_b128 v[88:91], v144 offset:17472
	v_pk_mul_f32 v[92:93], v[92:93], v[152:153]
	v_pk_mul_f32 v[100:101], v[100:101], v[152:153]
	v_pk_mul_f32 v[108:109], v[108:109], v[152:153]
	v_mfma_f32_16x16x32_bf16 v[62:65], v[148:151], v[62:65], v[92:95]
	v_exp_f32_e32 v120, v120
	v_exp_f32_e32 v121, v121
	v_exp_f32_e32 v122, v122
	v_mfma_f32_16x16x32_bf16 v[66:69], v[148:151], v[66:69], v[100:103]
	v_exp_f32_e32 v123, v123
	v_mfma_f32_16x16x32_bf16 v[70:73], v[148:151], v[70:73], v[108:111]
	s_waitcnt lgkmcnt(0)
	v_mfma_f32_16x16x32_bf16 v[42:45], v[88:91], v[42:45], v[58:61]
	v_mfma_f32_16x16x32_bf16 v[46:49], v[88:91], v[46:49], v[62:65]
	v_mfma_f32_16x16x32_bf16 v[50:53], v[88:91], v[50:53], v[66:69]
	v_mfma_f32_16x16x32_bf16 v[54:57], v[88:91], v[54:57], v[70:73]
	s_nop 4
	v_mul_f32_e64 v90, v122, v44
	v_mul_f32_e64 v91, v123, v45
	v_pk_mul_f32 v[88:89], v[120:121], v[42:43]
	v_cvt_pk_bf16_f32 v43, v90, v91
	v_cvt_pk_bf16_f32 v42, v88, v89
	v_add_u32_e32 v44, v138, v83
	v_pk_mul_f32 v[94:95], v[122:123], v[48:49]
	v_pk_mul_f32 v[92:93], v[120:121], v[46:47]
	ds_write_b64 v44, v[42:43] offset:54272
	v_cvt_pk_bf16_f32 v42, v92, v93
	v_cvt_pk_bf16_f32 v43, v94, v95
	v_pk_mul_f32 v[102:103], v[122:123], v[52:53]
	v_pk_mul_f32 v[100:101], v[120:121], v[50:51]
	ds_write_b64 v44, v[42:43] offset:58624
	v_cvt_pk_bf16_f32 v42, v100, v101
	v_cvt_pk_bf16_f32 v43, v102, v103
	v_pk_mul_f32 v[110:111], v[122:123], v[56:57]
	v_pk_mul_f32 v[108:109], v[120:121], v[54:55]
	ds_write_b64 v44, v[42:43] offset:62976
	v_cvt_pk_bf16_f32 v42, v108, v109
	v_cvt_pk_bf16_f32 v43, v110, v111
	v_add_u32_e32 v44, v138, v85
	ds_write_b64 v44, v[42:43] offset:62976
	ds_read_b128 v[42:45], v145
	ds_read_b128 v[46:49], v145 offset:512
	ds_read_b128 v[62:65], v146 offset:17408
	ds_read_b128 v[66:69], v142 offset:45056
	s_waitcnt lgkmcnt(3)
	v_mul_f32_e32 v42, 0x3fb8aa3b, v42
	v_mul_f32_e32 v43, 0x3fb8aa3b, v43
	v_mul_f32_e32 v44, 0x3fb8aa3b, v44
	v_mul_f32_e32 v45, 0x3fb8aa3b, v45
	v_exp_f32_e32 v58, v42
	v_exp_f32_e32 v59, v43
	v_exp_f32_e32 v60, v44
	v_exp_f32_e32 v61, v45
	s_waitcnt lgkmcnt(2)
	v_mul_f32_e32 v42, 0x3fb8aa3b, v46
	v_mul_f32_e32 v43, 0x3fb8aa3b, v47
	v_mul_f32_e32 v44, 0x3fb8aa3b, v48
	v_mul_f32_e32 v45, 0x3fb8aa3b, v49
	v_pk_mul_f32 v[48:49], v[98:99], v[60:61]
	v_pk_mul_f32 v[46:47], v[96:97], v[58:59]
	v_pk_mul_f32 v[52:53], v[106:107], v[60:61]
	v_pk_mul_f32 v[50:51], v[104:105], v[58:59]
	s_waitcnt lgkmcnt(0)
	v_mfma_f32_16x16x32_bf16 v[46:49], v[62:65], v[66:69], v[46:49]
	ds_read_b128 v[66:69], v142 offset:47360
	v_pk_mul_f32 v[56:57], v[114:115], v[60:61]
	v_pk_mul_f32 v[54:55], v[112:113], v[58:59]
	s_waitcnt lgkmcnt(0)
	v_mfma_f32_16x16x32_bf16 v[50:53], v[62:65], v[66:69], v[50:53]
	ds_read_b128 v[66:69], v142 offset:49664
	v_pk_mul_f32 v[60:61], v[118:119], v[60:61]
	v_pk_mul_f32 v[58:59], v[116:117], v[58:59]
	s_waitcnt lgkmcnt(0)
	v_mfma_f32_16x16x32_bf16 v[54:57], v[62:65], v[66:69], v[54:57]
	ds_read_b128 v[66:69], v142 offset:51968
	v_exp_f32_e32 v42, v42
	v_exp_f32_e32 v43, v43
	s_waitcnt lgkmcnt(0)
	v_mfma_f32_16x16x32_bf16 v[58:61], v[62:65], v[66:69], v[58:61]
	ds_read_b128 v[62:65], v146 offset:17472
	ds_read_b128 v[66:69], v142 offset:45120
	v_exp_f32_e32 v44, v44
	v_exp_f32_e32 v45, v45
	s_waitcnt lgkmcnt(0)
	v_mfma_f32_16x16x32_bf16 v[46:49], v[62:65], v[66:69], v[46:49]
	ds_read_b128 v[66:69], v142 offset:47424
	s_waitcnt lgkmcnt(0)
	v_mfma_f32_16x16x32_bf16 v[50:53], v[62:65], v[66:69], v[50:53]
	ds_read_b128 v[66:69], v142 offset:49728
	s_nop 3
	v_pk_mul_f32 v[98:99], v[44:45], v[48:49]
	v_pk_mul_f32 v[96:97], v[42:43], v[46:47]
	s_waitcnt lgkmcnt(0)
	v_mfma_f32_16x16x32_bf16 v[54:57], v[62:65], v[66:69], v[54:57]
	ds_read_b128 v[66:69], v142 offset:52032
	v_cvt_pk_bf16_f32 v46, v96, v97
	v_cvt_pk_bf16_f32 v47, v98, v99
	s_waitcnt lgkmcnt(0)
	v_mfma_f32_16x16x32_bf16 v[58:61], v[62:65], v[66:69], v[58:61]
	v_add_u32_e32 v48, v139, v83
	v_pk_mul_f32 v[106:107], v[44:45], v[52:53]
	v_pk_mul_f32 v[104:105], v[42:43], v[50:51]
	ds_write_b64 v48, v[46:47] offset:54272
	v_cvt_pk_bf16_f32 v46, v104, v105
	v_cvt_pk_bf16_f32 v47, v106, v107
	v_pk_mul_f32 v[114:115], v[44:45], v[56:57]
	v_pk_mul_f32 v[112:113], v[42:43], v[54:55]
	v_pk_mul_f32 v[118:119], v[44:45], v[60:61]
	v_pk_mul_f32 v[116:117], v[42:43], v[58:59]
	ds_write_b64 v48, v[46:47] offset:58624
	v_cvt_pk_bf16_f32 v46, v112, v113
	v_cvt_pk_bf16_f32 v47, v114, v115
	v_cvt_pk_bf16_f32 v42, v116, v117
	v_cvt_pk_bf16_f32 v43, v118, v119
	v_add_u32_e32 v44, v139, v85
	ds_write_b64 v48, v[46:47] offset:62976
	ds_write_b64 v44, v[42:43] offset:62976
	s_waitcnt lgkmcnt(0)
	s_barrier
	s_cbranch_scc0 .LBB0_516
	s_branch .LBB0_463
